# sample FOX cache stream per-wave: each wave loads/converts/stages only its own head, no workgroup barriers in the stream loop (on top of register double-buffering)
# speedup vs baseline: 1.0276x; 1.0133x over previous
; #define LDS_AS __attribute__((address_space(3)))
;     ...
;     const float* ck = (MODE == 0 ? p.cak : p.cbk) + (size_t)bb * PAST * 512;
;     const float* cv = (MODE == 0 ? p.cav : p.cbv) + (size_t)bb * PAST * 512;
;     const int ntc = (MODE == 1 ? (PAST / NSPLIT / 32) : 128), kbase = (MODE == 1 ? (PAST / NSPLIT) * split : 0);
;     const bool has_new = (MODE == 0) || (split == NSPLIT - 1);
;     const float* cseq = p.c2s + (size_t)(bb * 8 + ((tid >> 5) & 7)) * LSK;
;     float cref = 0.f;
;     if (MODE == 1 && tid < 256) cref = cseq[PAST];
;     constexpr int KOFF = 0, VOFF = 36864, BOFF = 73728, HSTR = 4608;
;     bool wdone = false, alldone = false;
;     if (has_new) {
;         __syncthreads();
;         const bf16_t* kb = p.u + ((size_t)ROWS_P + bb * 32) * NU + segb + 512;
; #pragma unroll
;         for (int i = 0; i < 4; ++i) {
;             const int id = tid + 512 * i, r = id >> 6, c = id & 63, hd = c >> 3, d = (c & 7) * 8;
;             const u32x4 kx = *(const u32x4*)(kb + (size_t)r * NU + c * 8);
;             const u32x4 vx = *(const u32x4*)(kb + (size_t)r * NU + 512 + c * 8);
;             *(LDS_AS u32x4*)(lb + KOFF + hd * HSTR + r * 144 + d * 2) = kx;
;             *(LDS_AS u32x4*)(lb + VOFF + hd * HSTR + r * 144 + d * 2) = vx;
;         }
;         if (MODE == 1 && tid < 256) *(LDS_AS float*)(lb + BOFF + tid * 4) = cref - cseq[PAST + (tid & 31)];
;         __syncthreads();
;         attn_subtile<MODE>(lb + KOFF + wave * HSTR, lb + VOFF + wave * HSTR, lb + BOFF + wave * 128, q, st, PAST, qpos, true, lane);
;         if (MODE == 0) { wdone = __all(st.l < -SB_THRESH); alldone = __syncthreads_and(wdone ? 1 : 0) != 0; }
;     }
;     if (!alldone) {
;         f32x4 tk[8], tv[8]; float tb = 0.f;
;         const int rot = (MODE == 1) ? ((bb * NSPLIT + split) * 5) % ntc : 0;
;         {
;             const int t0i = (ntc - 1 + rot) % ntc;
;             const float* kg = ck + (size_t)(kbase + 32 * t0i) * 512;
;             const float* vg = cv + (size_t)(kbase + 32 * t0i) * 512;
;             if (MODE == 1 && tid < 256) tb = cseq[kbase + 32 * t0i + (tid & 31)];
; #pragma unroll
;             for (int i = 0; i < 8; ++i) { const int id = tid + 512 * i; tk[i] = __builtin_nontemporal_load((const f32x4*)(kg + (size_t)id * 4)); tv[i] = __builtin_nontemporal_load((const f32x4*)(vg + (size_t)id * 4)); }
;         }
.LBB0_455:
	s_or_b64 exec, exec, s[34:35]
	s_ashr_i32 s7, s6, 31
	s_lshl_b64 s[34:35], s[6:7], 23
	s_add_u32 s36, s84, s34
	s_addc_u32 s37, s85, s35
	s_add_u32 s38, s86, s34
	s_addc_u32 s39, s87, s35
	s_ashr_i32 s31, s30, 31
	s_lshl_b64 s[30:31], s[30:31], 11
	s_add_u32 s34, s36, s30
	s_addc_u32 s35, s37, s31
	s_add_u32 s30, s38, s30
	v_ashrrev_i32_e32 v135, 31, v134
	s_addc_u32 s31, s39, s31
	v_lshlrev_b64 v[40:41], 4, v[134:135]
	v_lshl_add_u64 v[42:43], s[34:35], 0, v[40:41]
	v_lshl_add_u64 v[40:41], s[30:31], 0, v[40:41]
	v_ashrrev_i32_e32 v37, 31, v36
	global_load_dwordx4 v[68:71], v[40:41], off nt
	v_lshlrev_b64 v[40:41], 4, v[36:37]
	global_load_dwordx4 v[64:67], v[42:43], off nt
	v_lshl_add_u64 v[42:43], s[34:35], 0, v[40:41]
	v_lshl_add_u64 v[40:41], s[30:31], 0, v[40:41]
	v_ashrrev_i32_e32 v35, 31, v34
	global_load_dwordx4 v[76:79], v[40:41], off nt
	v_lshlrev_b64 v[40:41], 4, v[34:35]
	global_load_dwordx4 v[72:75], v[42:43], off nt
	v_lshl_add_u64 v[42:43], s[34:35], 0, v[40:41]
	v_lshl_add_u64 v[40:41], s[30:31], 0, v[40:41]
	v_ashrrev_i32_e32 v33, 31, v32
	global_load_dwordx4 v[84:87], v[40:41], off nt
	v_lshlrev_b64 v[40:41], 4, v[32:33]
	global_load_dwordx4 v[80:83], v[42:43], off nt
	v_lshl_add_u64 v[42:43], s[34:35], 0, v[40:41]
	v_lshl_add_u64 v[40:41], s[30:31], 0, v[40:41]
	global_load_dwordx4 v[92:95], v[40:41], off nt
	v_add_u32_e32 v40, 0x800, v134
	v_ashrrev_i32_e32 v41, 31, v40
	global_load_dwordx4 v[88:91], v[42:43], off nt
	v_lshlrev_b64 v[42:43], 4, v[40:41]
	v_lshl_add_u64 v[44:45], s[34:35], 0, v[42:43]
	v_lshl_add_u64 v[42:43], s[30:31], 0, v[42:43]
	global_load_dwordx4 v[100:103], v[42:43], off nt
	v_add_u32_e32 v42, 0xa00, v134
	v_ashrrev_i32_e32 v43, 31, v42
	global_load_dwordx4 v[96:99], v[44:45], off nt
	v_lshlrev_b64 v[44:45], 4, v[42:43]
	v_lshl_add_u64 v[46:47], s[34:35], 0, v[44:45]
	v_lshl_add_u64 v[44:45], s[30:31], 0, v[44:45]
	global_load_dwordx4 v[108:111], v[44:45], off nt
	v_add_u32_e32 v44, 0xc00, v134
	v_ashrrev_i32_e32 v45, 31, v44
	global_load_dwordx4 v[104:107], v[46:47], off nt
	v_lshlrev_b64 v[46:47], 4, v[44:45]
	s_waitcnt vmcnt(27)
	v_lshl_add_u64 v[112:113], s[34:35], 0, v[46:47]
	v_lshl_add_u64 v[46:47], s[30:31], 0, v[46:47]
	global_load_dwordx4 v[116:119], v[46:47], off nt
	v_add_u32_e32 v46, 0xe00, v134
	v_ashrrev_i32_e32 v47, 31, v46
	s_waitcnt vmcnt(25)
	v_lshlrev_b64 v[124:125], 4, v[46:47]
	v_lshl_add_u64 v[120:121], s[34:35], 0, v[124:125]
	v_lshl_add_u64 v[124:125], s[30:31], 0, v[124:125]
	global_load_dwordx4 v[112:115], v[112:113], off nt
	v_lshlrev_b64 v[160:161], 2, v[42:43]
	global_load_dwordx4 v[120:123], v[120:121], off nt
	v_and_b32_e32 v43, 64, v174
	global_load_dwordx4 v[124:127], v[124:125], off nt
	v_lshlrev_b64 v[158:159], 2, v[40:41]
	v_xor_b32_e32 v41, 32, v174
	v_add_u32_e32 v43, 64, v43
	v_cmp_lt_i32_e32 vcc, v41, v43
	v_lshlrev_b64 v[154:155], 2, v[34:35]
	v_lshlrev_b64 v[156:157], 2, v[32:33]
	v_bfe_u32 v33, v134, 4, 3
	v_lshlrev_b32_e32 v35, 3, v134
	v_cndmask_b32_e32 v41, v174, v41, vcc
	v_lshlrev_b64 v[150:151], 2, v[134:135]
	v_and_b32_e32 v35, 0x78, v35
	v_mul_u32_u24_e32 v33, 0x1200, v33
	v_lshlrev_b32_e32 v181, 2, v41
	v_lshrrev_b32_e32 v41, 2, v134
	v_lshlrev_b32_e32 v135, 2, v38
	v_add3_u32 v33, s62, v33, v35
	v_mul_lo_u32 v35, v136, s91
	v_and_b32_e32 v43, 16, v134
	v_and_or_b32 v38, v41, 3, v135
	v_lshlrev_b32_e32 v41, 2, v133
	v_add_u32_e32 v35, 0x100, v35
	v_and_or_b32 v41, v41, 12, v43
	v_ashrrev_i32_e32 v32, 7, v32
	v_lshlrev_b64 v[152:153], 2, v[36:37]
	v_lshlrev_b64 v[162:163], 2, v[44:45]
	s_add_i32 s30, s92, 0x100
	v_mad_u32_u24 v39, v176, s89, v35
	v_mad_u32_u24 v35, v38, s89, v35
	v_lshlrev_b32_e32 v38, 1, v41
	v_lshlrev_b32_e32 v41, 2, v134
	v_ashrrev_i32_e32 v43, 7, v134
	v_ashrrev_i32_e32 v36, 7, v36
	v_ashrrev_i32_e32 v34, 7, v34
	v_mul_lo_u32 v32, v32, s89
	v_ashrrev_i32_e32 v40, 7, v40
	v_ashrrev_i32_e32 v42, 7, v42
	v_ashrrev_i32_e32 v44, 7, v44
	v_ashrrev_i32_e32 v45, 7, v46
	v_lshlrev_b64 v[164:165], 2, v[46:47]
	v_lshl_add_u32 v37, v136, 7, s30
	v_mul_lo_u32 v43, v43, s89
	v_mul_lo_u32 v36, v36, s89
	v_mul_lo_u32 v34, v34, s89
	v_mul_lo_u32 v40, v40, s89
	v_mul_lo_u32 v42, v42, s89
	v_mul_lo_u32 v44, v44, s89
	v_mul_lo_u32 v45, v45, s89
	v_add_u32_e32 v185, v33, v32
	v_add_u32_e32 v32, 0x100, v41
	s_movk_i32 s42, 0x7c0
	v_add_u32_e32 v182, v33, v43
	v_add_u32_e32 v183, v33, v36
	v_add_u32_e32 v184, v33, v34
	v_add_u32_e32 v186, v33, v40
	v_add_u32_e32 v187, v33, v42
	v_add_u32_e32 v188, v33, v44
	v_add_u32_e32 v189, v33, v45
	v_add_u32_e32 v190, 0x12000, v32
	v_lshlrev_b64 v[150:151], 2, v[150:151]
	v_lshlrev_b64 v[152:153], 2, v[152:153]
	v_lshlrev_b64 v[154:155], 2, v[154:155]
	v_lshlrev_b64 v[156:157], 2, v[156:157]
	v_lshlrev_b64 v[158:159], 2, v[158:159]
	v_lshlrev_b64 v[160:161], 2, v[160:161]
	v_lshlrev_b64 v[162:163], 2, v[162:163]
	v_lshlrev_b64 v[164:165], 2, v[164:165]
	v_add_u32_e32 v191, v37, v130
	v_add_u32_e32 v130, v39, v130
	v_add_u32_e32 v192, v35, v38
	v_lshrrev_b32_e32 v32, 4, v174
	v_and_b32_e32 v33, 15, v174
	v_lshlrev_b32_e32 v34, 11, v32
	v_lshl_add_u32 v34, v136, 8, v34
	v_lshl_add_u32 v34, v33, 4, v34
	v_mov_b32_e32 v150, v34
	v_mov_b32_e32 v151, 0
	v_add_u32_e32 v152, 0x2000, v34
	v_mov_b32_e32 v153, 0
	v_add_u32_e32 v154, 0x4000, v34
	v_mov_b32_e32 v155, 0
	v_add_u32_e32 v156, 0x6000, v34
	v_mov_b32_e32 v157, 0
	v_add_u32_e32 v158, 0x8000, v34
	v_mov_b32_e32 v159, 0
	v_add_u32_e32 v160, 0xa000, v34
	v_mov_b32_e32 v161, 0
	v_add_u32_e32 v162, 0xc000, v34
	v_mov_b32_e32 v163, 0
	v_add_u32_e32 v164, 0xe000, v34
	v_mov_b32_e32 v165, 0
	v_mul_u32_u24_e32 v35, 0x1200, v136
	v_mad_u32_u24 v35, v32, s89, v35
	v_lshl_add_u32 v35, v33, 3, v35
	v_add_u32_e32 v35, 0x100, v35
	v_mov_b32_e32 v182, v35
	v_add_u32_e32 v183, 0x240, v35
	v_add_u32_e32 v184, 0x480, v35
	v_add_u32_e32 v185, 0x6c0, v35
	v_add_u32_e32 v186, 0x900, v35
	v_add_u32_e32 v187, 0xb40, v35
	v_add_u32_e32 v188, 0xd80, v35
	v_add_u32_e32 v189, 0xfc0, v35
	v_cmp_gt_u32_e64 s[0:1], 32, v174
	v_lshl_add_u32 v36, s6, 3, v136
	v_mul_u32_u24_e32 v36, 0x4080, v36
	v_mov_b32_e32 v37, 0
	v_lshl_add_u64 v[148:149], s[74:75], 0, v[36:37]
	v_lshlrev_b32_e32 v190, 2, v176
	v_lshl_add_u32 v190, v136, 7, v190
	v_add_u32_e32 v190, 0x12100, v190
	v_mov_b32_e32 v36, 0x4000
	v_lshl_add_u64 v[36:37], v[148:149], 0, v[36:37]
	global_load_dword v177, v[36:37], off
	s_add_i32 s30, s10, s42
	s_add_i32 s30, s30, 32
	s_and_b32 s30, s30, 0x3e0
	s_or_b32 s30, s30, s9
	s_and_saveexec_b64 s[34:35], s[0:1]
	s_cbranch_execz .Lss_z461
	v_or_b32_e32 v32, s30, v176
	v_ashrrev_i32_e32 v33, 31, v32
	v_lshl_add_u64 v[32:33], v[32:33], 2, v[148:149]
	global_load_dword v179, v[32:33], off
;     ...
;             const int t0i = (ntc - 1 + rot) % ntc;
;             const float* kg = ck + (size_t)(kbase + 32 * t0i) * 512;
;             const float* vg = cv + (size_t)(kbase + 32 * t0i) * 512;
;             if (MODE == 1 && tid < 256) tb = cseq[kbase + 32 * t0i + (tid & 31)];
; #pragma unroll
;             for (int i = 0; i < 8; ++i) { const int id = tid + 512 * i; tk[i] = __builtin_nontemporal_load((const f32x4*)(kg + (size_t)id * 4)); tv[i] = __builtin_nontemporal_load((const f32x4*)(vg + (size_t)id * 4)); }
;         }
.Lss_z461:
	s_or_b64 exec, exec, s[34:35]
	s_ashr_i32 s31, s30, 31
	s_lshl_b64 s[30:31], s[30:31], 11
	s_add_u32 s34, s36, s30
	s_addc_u32 s35, s37, s31
	s_add_u32 s30, s38, s30
	s_addc_u32 s31, s39, s31
	v_lshl_add_u64 v[32:33], s[34:35], 0, v[150:151]
	global_load_dwordx4 v[64:67], v[32:33], off nt
	v_lshl_add_u64 v[32:33], s[30:31], 0, v[150:151]
	global_load_dwordx4 v[68:71], v[32:33], off nt
	v_lshl_add_u64 v[32:33], s[34:35], 0, v[152:153]
	global_load_dwordx4 v[72:75], v[32:33], off nt
	v_lshl_add_u64 v[32:33], s[30:31], 0, v[152:153]
	global_load_dwordx4 v[76:79], v[32:33], off nt
	v_lshl_add_u64 v[32:33], s[34:35], 0, v[154:155]
	global_load_dwordx4 v[80:83], v[32:33], off nt
	v_lshl_add_u64 v[32:33], s[30:31], 0, v[154:155]
	global_load_dwordx4 v[84:87], v[32:33], off nt
	v_lshl_add_u64 v[32:33], s[34:35], 0, v[156:157]
	global_load_dwordx4 v[88:91], v[32:33], off nt
	v_lshl_add_u64 v[32:33], s[30:31], 0, v[156:157]
	global_load_dwordx4 v[92:95], v[32:33], off nt
	v_lshl_add_u64 v[32:33], s[34:35], 0, v[158:159]
	global_load_dwordx4 v[96:99], v[32:33], off nt
	v_lshl_add_u64 v[32:33], s[30:31], 0, v[158:159]
	global_load_dwordx4 v[100:103], v[32:33], off nt
	v_lshl_add_u64 v[32:33], s[34:35], 0, v[160:161]
	global_load_dwordx4 v[104:107], v[32:33], off nt
	v_lshl_add_u64 v[32:33], s[30:31], 0, v[160:161]
	global_load_dwordx4 v[108:111], v[32:33], off nt
	v_lshl_add_u64 v[32:33], s[34:35], 0, v[162:163]
	global_load_dwordx4 v[112:115], v[32:33], off nt
	v_lshl_add_u64 v[32:33], s[30:31], 0, v[162:163]
	global_load_dwordx4 v[116:119], v[32:33], off nt
	v_lshl_add_u64 v[32:33], s[34:35], 0, v[164:165]
	global_load_dwordx4 v[120:123], v[32:33], off nt
	v_lshl_add_u64 v[32:33], s[30:31], 0, v[164:165]
	global_load_dwordx4 v[124:127], v[32:33], off nt
	s_add_i32 s30, s10, s42
	s_and_b32 s30, s30, 0x3e0
	s_or_b32 s30, s30, s9
	s_and_saveexec_b64 s[34:35], s[0:1]
	s_cbranch_execz .Lss_p461
	v_or_b32_e32 v32, s30, v176
	v_ashrrev_i32_e32 v33, 31, v32
	v_lshl_add_u64 v[32:33], v[32:33], 2, v[148:149]
	global_load_dword v144, v[32:33], off

; #define LDS_AS __attribute__((address_space(3)))
; DI unsigned pk2(float a, float b) { f32x2 v = {a, b}; bf16x2v r = __builtin_convertvector(v, bf16x2v); return __builtin_bit_cast(unsigned, r); }
;     ...
;             __syncthreads();
; #pragma unroll
;             for (int i = 0; i < 8; ++i) {
;                 const int id = tid + 512 * i, r = id >> 7, c4 = id & 127, hd = c4 >> 4, d = (c4 & 15) * 4;
;                 *(LDS_AS u32x2*)(lb + KOFF + hd * HSTR + r * 144 + d * 2) = (u32x2){pk2(tk[i][0], tk[i][1]), pk2(tk[i][2], tk[i][3])};
;                 *(LDS_AS u32x2*)(lb + VOFF + hd * HSTR + r * 144 + d * 2) = (u32x2){pk2(tv[i][0], tv[i][1]), pk2(tv[i][2], tv[i][3])};
;             }
;             if (MODE == 1 && tid < 256) *(LDS_AS float*)(lb + BOFF + tid * 4) = cref - tb;
.LBB0_456:
	s_waitcnt vmcnt(30)
	v_cvt_pk_bf16_f32 v32, v64, v65
	v_cvt_pk_bf16_f32 v33, v66, v67
	v_cvt_pk_bf16_f32 v34, v68, v69
	v_cvt_pk_bf16_f32 v35, v70, v71
	ds_write2st64_b64 v182, v[32:33], v[34:35] offset1:72
	s_waitcnt vmcnt(28)
	v_cvt_pk_bf16_f32 v32, v72, v73
	v_cvt_pk_bf16_f32 v33, v74, v75
	v_cvt_pk_bf16_f32 v34, v76, v77
	v_cvt_pk_bf16_f32 v35, v78, v79
	ds_write2st64_b64 v183, v[32:33], v[34:35] offset1:72
	s_waitcnt vmcnt(26)
	v_cvt_pk_bf16_f32 v32, v80, v81
	v_cvt_pk_bf16_f32 v33, v82, v83
	v_cvt_pk_bf16_f32 v34, v84, v85
	v_cvt_pk_bf16_f32 v35, v86, v87
	ds_write2st64_b64 v184, v[32:33], v[34:35] offset1:72
	s_waitcnt vmcnt(24)
	v_cvt_pk_bf16_f32 v32, v88, v89
	v_cvt_pk_bf16_f32 v33, v90, v91
	v_cvt_pk_bf16_f32 v34, v92, v93
	v_cvt_pk_bf16_f32 v35, v94, v95
	ds_write2st64_b64 v185, v[32:33], v[34:35] offset1:72
	s_waitcnt vmcnt(22)
	v_cvt_pk_bf16_f32 v32, v96, v97
	v_cvt_pk_bf16_f32 v33, v98, v99
	v_cvt_pk_bf16_f32 v34, v100, v101
	v_cvt_pk_bf16_f32 v35, v102, v103
	ds_write2st64_b64 v186, v[32:33], v[34:35] offset1:72
	s_waitcnt vmcnt(20)
	v_cvt_pk_bf16_f32 v32, v104, v105
	v_cvt_pk_bf16_f32 v33, v106, v107
	v_cvt_pk_bf16_f32 v34, v108, v109
	v_cvt_pk_bf16_f32 v35, v110, v111
	ds_write2st64_b64 v187, v[32:33], v[34:35] offset1:72
	s_waitcnt vmcnt(18)
	v_cvt_pk_bf16_f32 v32, v112, v113
	v_cvt_pk_bf16_f32 v33, v114, v115
	v_cvt_pk_bf16_f32 v34, v116, v117
	v_cvt_pk_bf16_f32 v35, v118, v119
	ds_write2st64_b64 v188, v[32:33], v[34:35] offset1:72
	s_waitcnt vmcnt(17)
	v_cvt_pk_bf16_f32 v32, v120, v121
	v_cvt_pk_bf16_f32 v33, v122, v123
	s_waitcnt vmcnt(16)
	v_cvt_pk_bf16_f32 v34, v124, v125
	v_cvt_pk_bf16_f32 v35, v126, v127
	ds_write2st64_b64 v189, v[32:33], v[34:35] offset1:72
	s_and_saveexec_b64 s[30:31], s[0:1]
	v_sub_f32_e32 v32, v177, v179
	ds_write_b32 v190, v32
	s_or_b64 exec, exec, s[30:31]
	s_cmpk_lt_u32 s42, 0x420
	s_cbranch_scc1 .Lss_a462
	s_add_i32 s30, s10, s42
	s_sub_i32 s30, s30, 32
	s_and_b32 s30, s30, 0x3e0
	s_or_b32 s30, s30, s9
	s_and_saveexec_b64 s[34:35], s[0:1]
	s_cbranch_execz .Lss_a461
	v_or_b32_e32 v32, s30, v176
	v_ashrrev_i32_e32 v33, 31, v32
	v_lshl_add_u64 v[32:33], v[32:33], 2, v[148:149]
	global_load_dword v179, v[32:33], off

; #define LDS_AS __attribute__((address_space(3)))
; #define MFMA(a, b, c) __builtin_amdgcn_mfma_f32_32x32x16_bf16((a), (b), (c), 0, 0, 0)
; DI int crow(int i, int hh) { return (i & 3) + 8 * (i >> 2) + 4 * hh; }
; template <int MODE>
; DI void attn_subtile(LDS_AS const char* Kl, LDS_AS const char* Vl, LDS_AS const char* biasl, const bf16x8 (&q)[4], AttnState& st, int kpos0, int qpos, bool need_mask, int lane) {
;     ...
;     if (MODE == 1) {
; #pragma unroll
;         for (int g = 0; g < 4; ++g) { const f32x4 bv = *(LDS_AS const f32x4*)(biasl + (8 * g + 4 * hh) * 4); s[4 * g] = bv[0]; s[4 * g + 1] = bv[1]; s[4 * g + 2] = bv[2]; s[4 * g + 3] = bv[3]; }
;     } else {
; #pragma unroll
;         for (int i = 0; i < 16; ++i) s[i] = 0.f;
;     }
; #pragma unroll
;     for (int stp = 0; stp < 4; ++stp) { const bf16x8 kf = *(LDS_AS const bf16x8*)(Kl + l31 * 144 + (2 * stp + hh) * 16); s = MFMA(kf, q[stp], s); }
;     if (MODE == 1) {
;         if (need_mask) {
; #pragma unroll
;             for (int i = 0; i < 16; ++i) if (kpos0 + crow(i, hh) > qpos) s[i] = -INFINITY;
;         }
;         float mx = s[0];
; #pragma unroll
;         for (int i = 1; i < 16; ++i) mx = fmaxf(mx, s[i]);
;         mx = fmaxf(mx, __shfl_xor(mx, 32));
;         const float mn = fmaxf(st.m, mx);
;         if (__any(mn > st.m)) { const float a = __builtin_amdgcn_exp2f(st.m - mn); st.o0 = st.o0 * a; st.o1 = st.o1 * a; st.l *= a; }
;         st.m = mn;
;     ...
;             __builtin_amdgcn_sched_barrier(0);
;             __syncthreads();
;             if (!wdone) {
.Lss_a462:
	s_waitcnt lgkmcnt(0)
	ds_read_b128 v[194:197], v130
	ds_read_b128 v[32:35], v191
	ds_read_b128 v[36:39], v191 offset:32
	ds_read_b128 v[40:43], v191 offset:64
	ds_read_b128 v[44:47], v191 offset:96
	ds_read_b128 v[198:201], v130 offset:32
	s_waitcnt lgkmcnt(1)
	v_mfma_f32_32x32x16_bf16 v[32:47], v[194:197], v[56:59], v[32:47]
	s_waitcnt lgkmcnt(0)
	v_mfma_f32_32x32x16_bf16 v[32:47], v[198:201], v[48:51], v[32:47]
	ds_read_b128 v[194:197], v130 offset:64
	ds_read_b128 v[198:201], v130 offset:96
	s_waitcnt lgkmcnt(1)
	v_mfma_f32_32x32x16_bf16 v[32:47], v[194:197], v[52:55], v[32:47]
	s_waitcnt lgkmcnt(0)
	v_mfma_f32_32x32x16_bf16 v[32:47], v[198:201], v[60:63], v[32:47]
	s_nop 11
	v_max_f32_e32 v193, v33, v33
	v_max_f32_e32 v194, v32, v32
	v_max_f32_e32 v193, v194, v193
	v_max3_f32 v193, v193, v34, v35
	v_max3_f32 v193, v193, v36, v37
	v_max3_f32 v193, v193, v38, v39
	v_max3_f32 v193, v193, v40, v41
	v_max3_f32 v193, v193, v42, v43
	v_max3_f32 v193, v193, v44, v45
	v_max3_f32 v193, v193, v46, v47
	ds_bpermute_b32 v194, v181, v193
	s_waitcnt lgkmcnt(0)
	v_max3_f32 v193, v180, v193, v194
	v_cmp_gt_f32_e32 vcc, v193, v180
	s_cbranch_vccz .Lss_a464
	v_sub_f32_e32 v180, v180, v193
	v_exp_f32_e32 v180, v180
	s_nop 0
	v_pk_mul_f32 v[30:31], v[30:31], v[180:181] op_sel_hi:[1,0]
	v_pk_mul_f32 v[28:29], v[28:29], v[180:181] op_sel_hi:[1,0]
	v_pk_mul_f32 v[26:27], v[26:27], v[180:181] op_sel_hi:[1,0]
	v_pk_mul_f32 v[24:25], v[24:25], v[180:181] op_sel_hi:[1,0]
	v_pk_mul_f32 v[22:23], v[22:23], v[180:181] op_sel_hi:[1,0]
	v_pk_mul_f32 v[20:21], v[20:21], v[180:181] op_sel_hi:[1,0]
	v_pk_mul_f32 v[18:19], v[18:19], v[180:181] op_sel_hi:[1,0]
	v_pk_mul_f32 v[16:17], v[16:17], v[180:181] op_sel_hi:[1,0]
	v_pk_mul_f32 v[14:15], v[14:15], v[180:181] op_sel_hi:[1,0]
	v_pk_mul_f32 v[12:13], v[12:13], v[180:181] op_sel_hi:[1,0]
	v_pk_mul_f32 v[10:11], v[10:11], v[180:181] op_sel_hi:[1,0]
	v_pk_mul_f32 v[8:9], v[8:9], v[180:181] op_sel_hi:[1,0]
	v_pk_mul_f32 v[6:7], v[6:7], v[180:181] op_sel_hi:[1,0]
	v_pk_mul_f32 v[4:5], v[4:5], v[180:181] op_sel_hi:[1,0]
	v_pk_mul_f32 v[2:3], v[2:3], v[180:181] op_sel_hi:[1,0]
	v_pk_mul_f32 v[0:1], v[0:1], v[180:181] op_sel_hi:[1,0]
	v_mul_f32_e32 v178, v178, v180
; DI int crow(int i, int hh) { return (i & 3) + 8 * (i >> 2) + 4 * hh; }
; template <int MODE>
; DI void attn_subtile(LDS_AS const char* Kl, LDS_AS const char* Vl, LDS_AS const char* biasl, const bf16x8 (&q)[4], AttnState& st, int kpos0, int qpos, bool need_mask, int lane) {
;     ...
;         float mx = s[0];
; #pragma unroll
;         for (int i = 1; i < 16; ++i) mx = fmaxf(mx, s[i]);
;         mx = fmaxf(mx, __shfl_xor(mx, 32));
;         const float mn = fmaxf(st.m, mx);
;         if (__any(mn > st.m)) { const float a = __builtin_amdgcn_exp2f(st.m - mn); st.o0 = st.o0 * a; st.o1 = st.o1 * a; st.l *= a; }
;         st.m = mn;
;         float ps = 0.f;
; #pragma unroll
;         for (int i = 0; i < 16; ++i) { s[i] = __builtin_amdgcn_exp2f(s[i] - mn); ps += s[i]; }
;         st.l += ps;
;     } else {
;         f32x16 lk;
; #pragma unroll
;         for (int i = 0; i < 16; ++i) {
;             const float z = s[i];
;             const float e = __builtin_amdgcn_exp2f(-fabsf(z));
;             const float sp = __builtin_amdgcn_logf(1.0f + e);
;             float lkv = -fmaxf(z, 0.f) - sp;
;             float lsv = z + lkv;
;             if (need_mask && (kpos0 + crow(i, hh) >= qpos)) { lkv = 0.f; lsv = -INFINITY; }
;             lk[i] = lkv; s[i] = lsv;
;         }
;         float tot[4], suf1[4], suf0[4];
; #pragma unroll
;         for (int g = 0; g < 4; ++g) { suf1[g] = lk[4 * g + 3] + lk[4 * g + 2]; suf0[g] = suf1[g] + lk[4 * g + 1]; tot[g] = suf0[g] + lk[4 * g]; }
;         float pb[4], cs[4];
; #pragma unroll
;         for (int g = 0; g < 4; ++g) { pb[g] = __shfl_xor(tot[g], 32); cs[g] = tot[g] + pb[g]; }
;         const float S3 = 0.f, S2 = cs[3], S1 = S2 + cs[2], S0 = S1 + cs[1], total = S0 + cs[0];
;         const float Sg[4] = {S0, S1, S2, S3};
; #pragma unroll
;         for (int g = 0; g < 4; ++g) {
;             const float base = st.l + Sg[g] + (hh == 0 ? pb[g] : 0.f);
;             s[4 * g + 3] = __builtin_amdgcn_exp2f(s[4 * g + 3] + base);
;             s[4 * g + 2] = __builtin_amdgcn_exp2f(s[4 * g + 2] + (base + lk[4 * g + 3]));
;             s[4 * g + 1] = __builtin_amdgcn_exp2f(s[4 * g + 1] + (base + suf1[g]));
;             s[4 * g + 0] = __builtin_amdgcn_exp2f(s[4 * g + 0] + (base + suf0[g]));
;         }
;         st.l += total;
;     }
;     bf16x8 pf[2];
; #pragma unroll
;     for (int s2 = 0; s2 < 2; ++s2) {
;         u32x4 w;
.Lss_a464:
	v_sub_f32_e32 v32, v32, v193
	v_exp_f32_e32 v180, v32
	v_sub_f32_e32 v32, v33, v193
	v_exp_f32_e32 v194, v32
	v_sub_f32_e32 v32, v34, v193
	v_exp_f32_e32 v195, v32
	v_sub_f32_e32 v32, v35, v193
	v_exp_f32_e32 v196, v32
	v_sub_f32_e32 v33, v36, v193
	v_add_f32_e32 v32, 0, v180
	v_exp_f32_e32 v197, v33
	v_sub_f32_e32 v33, v37, v193
	v_add_f32_e32 v32, v194, v32
	v_exp_f32_e32 v198, v33
	v_sub_f32_e32 v33, v38, v193
	v_add_f32_e32 v32, v195, v32
	v_exp_f32_e32 v199, v33
	v_sub_f32_e32 v33, v39, v193
	v_add_f32_e32 v32, v196, v32
	v_exp_f32_e32 v39, v33
	v_sub_f32_e32 v33, v40, v193
	v_add_f32_e32 v32, v197, v32
	v_exp_f32_e32 v200, v33
	v_sub_f32_e32 v33, v41, v193
	v_add_f32_e32 v32, v198, v32
	v_exp_f32_e32 v201, v33
	v_sub_f32_e32 v33, v42, v193
	v_add_f32_e32 v32, v199, v32
	v_exp_f32_e32 v202, v33
	v_sub_f32_e32 v33, v43, v193
	v_add_f32_e32 v32, v39, v32
	v_exp_f32_e32 v203, v33
	v_add_f32_e32 v32, v200, v32
	v_add_f32_e32 v32, v201, v32
	v_add_f32_e32 v32, v202, v32
	v_add_f32_e32 v146, v203, v32
	ds_read_b64_tr_b16 v[32:33], v192 offset:36864
	ds_read_b64_tr_b16 v[34:35], v192 offset:38016
	ds_read_b64_tr_b16 v[42:43], v192 offset:38080
	ds_read_b64_tr_b16 v[40:41], v192 offset:36928
	v_sub_f32_e32 v36, v44, v193
	v_exp_f32_e32 v44, v36
	v_cvt_pk_bf16_f32 v36, v180, v194
	v_cvt_pk_bf16_f32 v37, v195, v196
	v_cvt_pk_bf16_f32 v38, v197, v198
	v_cvt_pk_bf16_f32 v39, v199, v39
	v_sub_f32_e32 v47, v47, v193
	v_exp_f32_e32 v47, v47
	s_waitcnt lgkmcnt(2)
	v_mfma_f32_32x32x16_bf16 v[16:31], v[32:35], v[36:39], v[16:31]
	v_sub_f32_e32 v32, v45, v193
	v_exp_f32_e32 v45, v32
	v_sub_f32_e32 v32, v46, v193
	v_exp_f32_e32 v46, v32
	ds_read_b64_tr_b16 v[32:33], v192 offset:39168
	ds_read_b64_tr_b16 v[34:35], v192 offset:40320
	s_sub_i32 s42, s42, 32
	s_cmpk_eq_i32 s42, 0x3c0
	s_waitcnt lgkmcnt(2)
	v_mfma_f32_32x32x16_bf16 v[0:15], v[40:43], v[36:39], v[0:15]
	ds_read_b64_tr_b16 v[42:43], v192 offset:40384
	ds_read_b64_tr_b16 v[40:41], v192 offset:39232
	v_cvt_pk_bf16_f32 v36, v200, v201
	v_cvt_pk_bf16_f32 v37, v202, v203
	v_cvt_pk_bf16_f32 v38, v44, v45
	v_cvt_pk_bf16_f32 v39, v46, v47
	s_waitcnt lgkmcnt(2)
	s_nop 0
	v_mfma_f32_32x32x16_bf16 v[16:31], v[32:35], v[36:39], v[16:31]
	v_add_f32_e32 v32, v44, v146
	v_add_f32_e32 v32, v45, v32
	v_add_f32_e32 v32, v46, v32
	v_add_f32_e32 v32, v47, v32
	v_add_f32_e32 v178, v32, v178
	s_waitcnt lgkmcnt(0)
	v_mfma_f32_32x32x16_bf16 v[0:15], v[40:43], v[36:39], v[0:15]
	v_mov_b32_e32 v180, v193
	s_cmpk_eq_i32 s42, 0x3e0
	s_cbranch_scc1 .Lss_blast
	s_waitcnt vmcnt(30)
	v_cvt_pk_bf16_f32 v32, v204, v205
	v_cvt_pk_bf16_f32 v33, v206, v207
	v_cvt_pk_bf16_f32 v34, v208, v209
	v_cvt_pk_bf16_f32 v35, v210, v211
	ds_write2st64_b64 v182, v[32:33], v[34:35] offset1:72
	s_waitcnt vmcnt(28)
	v_cvt_pk_bf16_f32 v32, v212, v213
	v_cvt_pk_bf16_f32 v33, v214, v215
	v_cvt_pk_bf16_f32 v34, v216, v217
	v_cvt_pk_bf16_f32 v35, v218, v219
	ds_write2st64_b64 v183, v[32:33], v[34:35] offset1:72
	s_waitcnt vmcnt(26)
	v_cvt_pk_bf16_f32 v32, v220, v221
	v_cvt_pk_bf16_f32 v33, v222, v223
	v_cvt_pk_bf16_f32 v34, v224, v225
	v_cvt_pk_bf16_f32 v35, v226, v227
	ds_write2st64_b64 v184, v[32:33], v[34:35] offset1:72
	s_waitcnt vmcnt(24)
	v_cvt_pk_bf16_f32 v32, v228, v229
	v_cvt_pk_bf16_f32 v33, v230, v231
	v_cvt_pk_bf16_f32 v34, v232, v233
	v_cvt_pk_bf16_f32 v35, v234, v235
	ds_write2st64_b64 v185, v[32:33], v[34:35] offset1:72
	s_waitcnt vmcnt(22)
	v_cvt_pk_bf16_f32 v32, v236, v237
	v_cvt_pk_bf16_f32 v33, v238, v239
	v_cvt_pk_bf16_f32 v34, v240, v241
	v_cvt_pk_bf16_f32 v35, v242, v243
	ds_write2st64_b64 v186, v[32:33], v[34:35] offset1:72
	s_waitcnt vmcnt(20)
	v_cvt_pk_bf16_f32 v32, v244, v245
	v_cvt_pk_bf16_f32 v33, v246, v247
	v_cvt_pk_bf16_f32 v34, v248, v249
	v_cvt_pk_bf16_f32 v35, v250, v251
	ds_write2st64_b64 v187, v[32:33], v[34:35] offset1:72
	s_waitcnt vmcnt(18)
	v_cvt_pk_bf16_f32 v32, v252, v253
	v_cvt_pk_bf16_f32 v33, v254, v255
	v_cvt_pk_bf16_f32 v34, v140, v141
	v_cvt_pk_bf16_f32 v35, v142, v143
	ds_write2st64_b64 v188, v[32:33], v[34:35] offset1:72
	s_waitcnt vmcnt(17)
	v_cvt_pk_bf16_f32 v32, v166, v167
	v_cvt_pk_bf16_f32 v33, v168, v169
	s_waitcnt vmcnt(16)
	v_cvt_pk_bf16_f32 v34, v170, v171
	v_cvt_pk_bf16_f32 v35, v172, v173
	ds_write2st64_b64 v189, v[32:33], v[34:35] offset1:72
	s_branch .Lss_bw
.Lss_blast:
	s_waitcnt vmcnt(14)
	v_cvt_pk_bf16_f32 v32, v204, v205
	v_cvt_pk_bf16_f32 v33, v206, v207
	v_cvt_pk_bf16_f32 v34, v208, v209
	v_cvt_pk_bf16_f32 v35, v210, v211
	ds_write2st64_b64 v182, v[32:33], v[34:35] offset1:72
	s_waitcnt vmcnt(12)
	v_cvt_pk_bf16_f32 v32, v212, v213
	v_cvt_pk_bf16_f32 v33, v214, v215
	v_cvt_pk_bf16_f32 v34, v216, v217
	v_cvt_pk_bf16_f32 v35, v218, v219
	ds_write2st64_b64 v183, v[32:33], v[34:35] offset1:72
	s_waitcnt vmcnt(10)
	v_cvt_pk_bf16_f32 v32, v220, v221
	v_cvt_pk_bf16_f32 v33, v222, v223
	v_cvt_pk_bf16_f32 v34, v224, v225
	v_cvt_pk_bf16_f32 v35, v226, v227
	ds_write2st64_b64 v184, v[32:33], v[34:35] offset1:72
	s_waitcnt vmcnt(8)
	v_cvt_pk_bf16_f32 v32, v228, v229
	v_cvt_pk_bf16_f32 v33, v230, v231
	v_cvt_pk_bf16_f32 v34, v232, v233
	v_cvt_pk_bf16_f32 v35, v234, v235
	ds_write2st64_b64 v185, v[32:33], v[34:35] offset1:72
	s_waitcnt vmcnt(6)
	v_cvt_pk_bf16_f32 v32, v236, v237
	v_cvt_pk_bf16_f32 v33, v238, v239
	v_cvt_pk_bf16_f32 v34, v240, v241
	v_cvt_pk_bf16_f32 v35, v242, v243
	ds_write2st64_b64 v186, v[32:33], v[34:35] offset1:72
	s_waitcnt vmcnt(4)
	v_cvt_pk_bf16_f32 v32, v244, v245
	v_cvt_pk_bf16_f32 v33, v246, v247
	v_cvt_pk_bf16_f32 v34, v248, v249
	v_cvt_pk_bf16_f32 v35, v250, v251
	ds_write2st64_b64 v187, v[32:33], v[34:35] offset1:72
	s_waitcnt vmcnt(2)
	v_cvt_pk_bf16_f32 v32, v252, v253
	v_cvt_pk_bf16_f32 v33, v254, v255
	v_cvt_pk_bf16_f32 v34, v140, v141
	v_cvt_pk_bf16_f32 v35, v142, v143
	ds_write2st64_b64 v188, v[32:33], v[34:35] offset1:72
	s_waitcnt vmcnt(1)
	v_cvt_pk_bf16_f32 v32, v166, v167
	v_cvt_pk_bf16_f32 v33, v168, v169
	s_waitcnt vmcnt(0)
	v_cvt_pk_bf16_f32 v34, v170, v171
	v_cvt_pk_bf16_f32 v35, v172, v173
	ds_write2st64_b64 v189, v[32:33], v[34:35] offset1:72
